# POOLMIX: the first 16 weight-fragment loads of the MFMA stage issued before the post-pooling barrier (were issued after it: exposed L2 round trip per unit)
# speedup vs baseline: 1.0016x; 1.0016x over previous
.LBB0_314:
	v_mov_b64_e32 v[226:227], v[210:211]
	global_load_dwordx4 v[8:11], v[226:227], off
	v_add_co_u32_e32 v2, vcc, 0x2000, v226
	s_mov_b32 s81, s80
	s_nop 0
	v_addc_co_u32_e32 v3, vcc, 0, v227, vcc
	v_add_co_u32_e32 v4, vcc, 0x4000, v226
	global_load_dwordx4 v[12:15], v[2:3], off
	s_nop 0
	v_addc_co_u32_e32 v5, vcc, 0, v227, vcc
	v_add_co_u32_e32 v6, vcc, 0x6000, v226
	global_load_dwordx4 v[16:19], v[4:5], off
	s_nop 0
	v_addc_co_u32_e32 v7, vcc, 0, v227, vcc
	v_add_co_u32_e32 v28, vcc, 0x8000, v226
	global_load_dwordx4 v[20:23], v[6:7], off
	s_nop 0
	v_addc_co_u32_e32 v29, vcc, 0, v227, vcc
	v_add_co_u32_e32 v30, vcc, 0xa000, v226
	global_load_dwordx4 v[24:27], v[28:29], off
	s_nop 0
	v_addc_co_u32_e32 v31, vcc, 0, v227, vcc
	v_add_co_u32_e32 v32, vcc, 0xc000, v226
	global_load_dwordx4 v[132:135], v[30:31], off
	s_nop 0
	v_addc_co_u32_e32 v33, vcc, 0, v227, vcc
	global_load_dwordx4 v[136:139], v[32:33], off
	v_add_co_u32_e32 v34, vcc, 0xe000, v226
	s_mov_b32 s82, s80
	s_nop 0
	v_addc_co_u32_e32 v35, vcc, 0, v227, vcc
	global_load_dwordx4 v[140:143], v[34:35], off
	global_load_dwordx4 v[100:103], v[226:227], off offset:1024
	global_load_dwordx4 v[104:107], v[2:3], off offset:1024
	global_load_dwordx4 v[108:111], v[4:5], off offset:1024
	global_load_dwordx4 v[112:115], v[6:7], off offset:1024
	global_load_dwordx4 v[116:119], v[28:29], off offset:1024
	global_load_dwordx4 v[120:123], v[30:31], off offset:1024
	global_load_dwordx4 v[124:127], v[32:33], off offset:1024
	global_load_dwordx4 v[128:131], v[34:35], off offset:1024
	s_waitcnt vmcnt(16) lgkmcnt(0)
	s_barrier
	ds_read_b128 v[28:31], v243
	s_mov_b32 s83, s80
	v_mov_b64_e32 v[4:5], s[80:81]
	v_mov_b64_e32 v[72:73], s[80:81]
	v_mov_b64_e32 v[76:77], s[80:81]
	v_mov_b64_e32 v[80:81], s[80:81]
	v_mov_b64_e32 v[86:87], s[82:83]
	v_mov_b64_e32 v[90:91], s[82:83]
	v_mov_b64_e32 v[94:95], s[82:83]
	v_mov_b64_e32 v[98:99], s[82:83]
	v_mov_b64_e32 v[6:7], s[82:83]
	s_and_b64 vcc, exec, s[42:43]
	v_mov_b64_e32 v[74:75], s[82:83]
	v_mov_b64_e32 v[78:79], s[82:83]
	v_mov_b64_e32 v[82:83], s[82:83]
	v_mov_b64_e32 v[84:85], s[80:81]
	v_mov_b64_e32 v[88:89], s[80:81]
	v_mov_b64_e32 v[92:93], s[80:81]
	v_mov_b64_e32 v[96:97], s[80:81]
	s_waitcnt vmcnt(15) lgkmcnt(0)
	v_mfma_f32_16x16x32_bf16 v[144:147], v[8:11], v[28:31], 0
	s_waitcnt vmcnt(14)
	v_mfma_f32_16x16x32_bf16 v[156:159], v[12:15], v[28:31], 0
	s_waitcnt vmcnt(13)
	v_mfma_f32_16x16x32_bf16 v[160:163], v[16:19], v[28:31], 0
	s_waitcnt vmcnt(12)
	v_mfma_f32_16x16x32_bf16 v[172:175], v[20:23], v[28:31], 0
	s_waitcnt vmcnt(11)
	v_mfma_f32_16x16x32_bf16 v[168:171], v[24:27], v[28:31], 0
	s_waitcnt vmcnt(10)
	v_mfma_f32_16x16x32_bf16 v[164:167], v[132:135], v[28:31], 0
	s_waitcnt vmcnt(9)
	v_mfma_f32_16x16x32_bf16 v[152:155], v[136:139], v[28:31], 0
	s_waitcnt vmcnt(8)
	v_mfma_f32_16x16x32_bf16 v[148:151], v[140:143], v[28:31], 0
	s_cbranch_vccz .LBB0_316
	ds_read_b128 v[2:5], v243 offset:33024
	s_waitcnt lgkmcnt(0)
	v_mfma_f32_16x16x32_bf16 v[96:99], v[8:11], v[2:5], 0
	v_mfma_f32_16x16x32_bf16 v[92:95], v[12:15], v[2:5], 0
	v_mfma_f32_16x16x32_bf16 v[88:91], v[16:19], v[2:5], 0
	v_mfma_f32_16x16x32_bf16 v[84:87], v[20:23], v[2:5], 0
	v_mfma_f32_16x16x32_bf16 v[80:83], v[24:27], v[2:5], 0
	v_mfma_f32_16x16x32_bf16 v[76:79], v[132:135], v[2:5], 0
	v_mfma_f32_16x16x32_bf16 v[72:75], v[136:139], v[2:5], 0
	v_mfma_f32_16x16x32_bf16 v[4:7], v[140:143], v[2:5], 0
